# MLA attention fast path v2: running row max folded into the QK accumulator init (C=-m), lazy rescale (reference max kept while row max within 2^8), per-lane threshold test; 5-buffer LDS prefetch; next
# speedup vs baseline: 1.0709x; 1.0212x over previous
.LBB0_763:
	s_and_b32 s4, s77, 1
	s_add_i32 s5, s77, s4
	s_sub_i32 s4, 0, s4
	s_xor_b32 s4, s2, s4
	s_mul_i32 s5, s5, s30
	s_add_i32 s4, s5, s4
	s_cmpk_gt_i32 s4, 0x1ff
	s_cbranch_scc1 .LBB0_762
	s_and_b32 s86, s4, 7
	s_mul_i32 s5, s86, 0x180
	s_add_u32 s10, s40, s5
	s_addc_u32 s11, s60, 0
	s_mul_i32 s5, s86, 0x600000
	s_add_u32 s6, s61, s5
	s_addc_u32 s7, s72, 0
	s_lshl_b32 s5, s86, 22
	s_add_u32 s8, s73, s5
	v_mov_b32_e32 v22, v162
	s_addc_u32 s9, s74, 0
	s_lshl_b32 s4, s4, 5
	s_and_b32 s54, s4, 0xffffff00
	v_ashrrev_i32_e32 v0, 1, v22
	v_and_b32_e32 v0, 0xffffffe0, v0
	v_subrev_u32_e32 v38, s54, v0
	v_and_b32_e32 v36, 31, v22
	v_add_u32_e32 v186, 0x3f00, v38
	v_bfe_u32 v37, v22, 5, 1
	v_or_b32_e32 v158, v186, v36
	s_mov_b32 s20, 0
	s_mov_b32 s21, 0
	v_readfirstlane_b32 s12, v186
	s_mov_b32 s15, 0
	s_mov_b32 s19, 0
	s_nop 3
	s_bitcmp0_b32 s12, 7
	s_cselect_b32 s14, 1, 0
	v_mov_b64_e32 v[2:3], s[10:11]
	v_mad_i64_i32 v[2:3], s[4:5], v158, s45, v[2:3]
	v_lshlrev_b32_e32 v0, 4, v37
	v_lshl_add_u64 v[2:3], v[2:3], 0, v[0:1]
	global_load_dwordx4 v[82:85], v[2:3], off
	global_load_dwordx4 v[86:89], v[2:3], off offset:32
	global_load_dwordx4 v[90:93], v[2:3], off offset:64
	global_load_dwordx4 v[94:97], v[2:3], off offset:96
	global_load_dwordx4 v[98:101], v[2:3], off offset:128
	global_load_dwordx4 v[102:105], v[2:3], off offset:160
	global_load_dwordx4 v[106:109], v[2:3], off offset:192
	global_load_dwordx4 v[110:113], v[2:3], off offset:224
	global_load_dwordx4 v[114:117], v[2:3], off offset:256
	global_load_dwordx4 v[118:121], v[2:3], off offset:288
	global_load_dwordx4 v[122:125], v[2:3], off offset:320
	global_load_dwordx4 v[126:129], v[2:3], off offset:352
	v_add_u32_e32 v24, 0x200, v22
	v_ashrrev_i32_e32 v25, 31, v24
	v_ashrrev_i32_e32 v23, 31, v22
	v_lshrrev_b32_e32 v18, 29, v25
	v_lshrrev_b32_e32 v12, 29, v23
	v_add_u32_e32 v20, v24, v18
	v_add_u32_e32 v14, v22, v12
	v_ashrrev_i32_e32 v32, 3, v20
	v_and_b32_e32 v20, -8, v20
	v_lshlrev_b64 v[166:167], 4, v[24:25]
	v_add_u32_e32 v26, 0x400, v22
	v_ashrrev_i32_e32 v28, 3, v14
	v_and_b32_e32 v14, -8, v14
	v_ashrrev_i32_e32 v33, 31, v32
	v_sub_u32_e32 v25, v24, v20
	v_lshlrev_b64 v[160:161], 4, v[22:23]
	v_ashrrev_i32_e32 v27, 31, v26
	v_ashrrev_i32_e32 v29, 31, v28
	v_sub_u32_e32 v23, v22, v14
	v_lshlrev_b64 v[174:175], 15, v[32:33]
	v_lshlrev_b32_e32 v176, 3, v25
	v_lshlrev_b64 v[168:169], 4, v[26:27]
	v_lshlrev_b64 v[170:171], 15, v[28:29]
	v_lshlrev_b32_e32 v172, 3, v23
	v_lshl_add_u64 v[18:19], s[8:9], 0, v[174:175]
	v_ashrrev_i32_e32 v177, 31, v176
	v_lshl_add_u64 v[2:3], s[6:7], 0, v[160:161]
	v_lshl_add_u64 v[6:7], s[6:7], 0, v[166:167]
	v_lshl_add_u64 v[10:11], s[6:7], 0, v[168:169]
	v_lshl_add_u64 v[12:13], s[8:9], 0, v[170:171]
	v_ashrrev_i32_e32 v173, 31, v172
	v_lshl_add_u64 v[34:35], v[176:177], 1, v[18:19]
	global_load_dwordx4 v[2:5], v[2:3], off
	s_nop 0
	global_load_dwordx4 v[6:9], v[6:7], off
	v_lshl_add_u64 v[30:31], v[172:173], 1, v[12:13]
	global_load_dwordx4 v[10:13], v[10:11], off
	s_nop 0
	global_load_dwordx4 v[14:17], v[30:31], off
	global_load_dwordx4 v[18:21], v[34:35], off
	s_sub_i32 s4, 0x4000, s54
	v_and_b32_e32 v27, 63, v22
	v_ashrrev_i32_e32 v159, 31, v158
	v_mul_hi_i32 v29, v22, s29
	v_lshrrev_b32_e32 v33, 31, v29
	v_ashrrev_i32_e32 v29, 2, v29
	v_add_u32_e32 v29, v29, v33
	v_mul_lo_u32 v187, v29, s48
	v_mul_lo_u32 v29, v29, 24
	v_sub_u32_e32 v22, v22, v29
	v_lshlrev_b32_e32 v188, 4, v22
	v_add3_u32 v22, s78, v187, v188
	s_waitcnt vmcnt(4)
	ds_write_b128 v22, v[2:5]
	v_mul_hi_i32 v2, v24, s29
	v_lshrrev_b32_e32 v3, 31, v2
	v_ashrrev_i32_e32 v2, 2, v2
	v_add_u32_e32 v2, v2, v3
	v_mul_lo_u32 v189, v2, s48
	v_mul_lo_u32 v2, v2, 24
	v_sub_u32_e32 v2, v24, v2
	v_lshlrev_b32_e32 v190, 4, v2
	v_add3_u32 v2, s78, v189, v190
	s_waitcnt vmcnt(3)
	ds_write_b128 v2, v[6:9]
	v_mul_hi_i32 v2, v26, s29
	v_lshrrev_b32_e32 v3, 31, v2
	v_ashrrev_i32_e32 v2, 2, v2
	v_add_u32_e32 v2, v2, v3
	v_mul_lo_u32 v191, v2, s48
	v_mul_lo_u32 v2, v2, 24
	v_sub_u32_e32 v2, v26, v2
	v_lshlrev_b32_e32 v192, 4, v2
	s_movk_i32 s5, 0x90
	v_add3_u32 v2, s78, v191, v192
	v_mul_lo_u32 v193, v28, s5
	v_lshlrev_b32_e32 v194, 4, v23
	s_waitcnt vmcnt(2)
	ds_write_b128 v2, v[10:13]
	v_add3_u32 v2, s78, v193, v194
	v_mul_lo_u32 v195, v32, s5
	v_lshlrev_b32_e32 v196, 4, v25
	s_add_u32 s10, s6, 0x6000
	s_waitcnt vmcnt(1)
	ds_write_b128 v2, v[14:17] offset:51200
	v_add3_u32 v2, s78, v195, v196
	s_addc_u32 s11, s7, 0
	s_waitcnt vmcnt(0)
	ds_write_b128 v2, v[18:21] offset:51200
	v_lshl_add_u64 v[2:3], s[10:11], 0, v[160:161]
	global_load_dwordx4 v[130:133], v[2:3], off
	v_lshl_add_u64 v[2:3], s[10:11], 0, v[166:167]
	global_load_dwordx4 v[134:137], v[2:3], off
	v_lshl_add_u64 v[2:3], s[10:11], 0, v[168:169]
	global_load_dwordx4 v[138:141], v[2:3], off
	global_load_dwordx4 v[142:145], v[30:31], off offset:128
	global_load_dwordx4 v[146:149], v[34:35], off offset:128
	s_movk_i32 s49, 0x90
	s_lshr_b32 s87, s4, 6
	v_mul_u32_u24_e32 v2, 0x190, v36
	v_add3_u32 v202, s78, v2, v0
	v_lshlrev_b32_e32 v2, 2, v27
	v_mov_b32_e32 v50, v1
	v_mov_b32_e32 v51, v1
	v_add_u32_e32 v201, 0x3f3f, v38
	v_add_u32_e32 v203, 0x3f1f, v38
	v_lshlrev_b32_e32 v197, 2, v37
	v_xor_b32_e32 v198, 0x80, v2
	v_mul_u32_u24_e32 v200, 0x90, v36
	v_mov_b32_e32 v52, v1
	v_mov_b32_e32 v53, v1
	v_mov_b32_e32 v54, v1
	v_mov_b32_e32 v55, v1
	v_mov_b32_e32 v56, v1
	v_mov_b32_e32 v57, v1
	v_mov_b32_e32 v58, v1
	v_mov_b32_e32 v59, v1
	v_mov_b32_e32 v60, v1
	v_mov_b32_e32 v61, v1
	v_mov_b32_e32 v62, v1
	v_mov_b32_e32 v63, v1
	v_mov_b32_e32 v64, v1
	v_mov_b32_e32 v65, v1
	v_readlane_b32 s5, v246, 59
	v_mov_b64_e32 v[34:35], v[50:51]
	v_mov_b64_e32 v[18:19], v[50:51]
	v_mov_b64_e32 v[2:3], v[50:51]
	s_mov_b32 s4, 0
	v_mov_b32_e32 v199, 0
	v_mov_b32_e32 v206, 0xf149f2ca
	v_mov_b32_e32 v209, s5
	v_mov_b32_e32 v154, 0
	v_mov_b32_e32 v155, 0
	v_mov_b32_e32 v156, 0
	v_mov_b32_e32 v157, 0
	v_mov_b32_e32 v150, 0
	v_mov_b32_e32 v151, 0
	v_mov_b32_e32 v152, 0
	v_mov_b32_e32 v153, 0
	v_mov_b64_e32 v[36:37], v[52:53]
	v_mov_b64_e32 v[38:39], v[54:55]
	v_mov_b64_e32 v[40:41], v[56:57]
	v_mov_b64_e32 v[42:43], v[58:59]
	v_mov_b64_e32 v[44:45], v[60:61]
	v_mov_b64_e32 v[46:47], v[62:63]
	v_mov_b64_e32 v[48:49], v[64:65]
	v_mov_b64_e32 v[20:21], v[52:53]
	v_mov_b64_e32 v[22:23], v[54:55]
	v_mov_b64_e32 v[24:25], v[56:57]
	v_mov_b64_e32 v[26:27], v[58:59]
	v_mov_b64_e32 v[28:29], v[60:61]
	v_mov_b64_e32 v[30:31], v[62:63]
	v_mov_b64_e32 v[32:33], v[64:65]
	v_mov_b64_e32 v[4:5], v[52:53]
	v_mov_b64_e32 v[6:7], v[54:55]
	v_mov_b64_e32 v[8:9], v[56:57]
	v_mov_b64_e32 v[10:11], v[58:59]
	v_mov_b64_e32 v[12:13], v[60:61]
	v_mov_b64_e32 v[14:15], v[62:63]
	v_mov_b64_e32 v[16:17], v[64:65]
	s_waitcnt lgkmcnt(0)
	s_barrier
	s_and_b32 s5, s4, 1
	s_add_i32 s88, s4, 1
	s_cmp_ge_u32 s88, s87
	s_cbranch_scc1 .LBB0_766

.Lmla_tail:
	s_mov_b32 s21, 1
	s_xor_b64 s[4:5], s[10:11], -1
	s_mov_b32 s90, 1
	s_mov_b64 s[10:11], 0
	s_and_b64 vcc, exec, s[4:5]
	s_cbranch_vccnz .LBB0_776
.LBB0_772:
	s_lshl_b32 s4, s90, 5
	s_or_b32 s91, s4, s54
	s_add_i32 s13, s91, 31
	s_cmp_le_i32 s13, s12
	s_cselect_b32 s13, s21, 0
	s_cmp_lg_u32 s13, 0
	s_cbranch_scc1 .Lmla_fast
	s_mov_b32 s20, 0
	v_cmp_le_i32_e32 vcc, s91, v201
	s_and_saveexec_b64 s[82:83], vcc
	s_cbranch_execz .LBB0_771
	s_or_b32 s4, s91, 31
	v_subrev_u32_e32 v66, s4, v186
	v_cmp_gt_i32_e32 vcc, 2.0, v66
	s_and_saveexec_b64 s[84:85], vcc
	s_cbranch_execz .LBB0_770
	s_mul_i32 s5, s90, 0x3200
	v_add_u32_e32 v205, s5, v204
	ds_read_b128 v[66:69], v205
	ds_read_b128 v[210:213], v205 offset:32
	ds_read_b128 v[214:217], v205 offset:64
	s_waitcnt lgkmcnt(2)
	v_mfma_f32_32x32x16_bf16 v[66:81], v[66:69], v[82:85], 0
	ds_read_b128 v[218:221], v205 offset:96
	s_waitcnt lgkmcnt(2)
	v_mfma_f32_32x32x16_bf16 v[66:81], v[210:213], v[86:89], v[66:81]
	ds_read_b128 v[210:213], v205 offset:128
	s_waitcnt lgkmcnt(2)
	v_mfma_f32_32x32x16_bf16 v[66:81], v[214:217], v[90:93], v[66:81]
	ds_read_b128 v[214:217], v205 offset:160
	s_waitcnt lgkmcnt(2)
	v_mfma_f32_32x32x16_bf16 v[66:81], v[218:221], v[94:97], v[66:81]
	ds_read_b128 v[218:221], v205 offset:192
	s_waitcnt lgkmcnt(2)
	v_mfma_f32_32x32x16_bf16 v[66:81], v[210:213], v[98:101], v[66:81]
	ds_read_b128 v[210:213], v205 offset:224
	s_waitcnt lgkmcnt(2)
	v_mfma_f32_32x32x16_bf16 v[66:81], v[214:217], v[102:105], v[66:81]
	ds_read_b128 v[214:217], v205 offset:256
	s_waitcnt lgkmcnt(2)
	v_mfma_f32_32x32x16_bf16 v[66:81], v[218:221], v[106:109], v[66:81]
	ds_read_b128 v[218:221], v205 offset:288
	s_waitcnt lgkmcnt(2)
	v_mfma_f32_32x32x16_bf16 v[66:81], v[210:213], v[110:113], v[66:81]
	ds_read_b128 v[210:213], v205 offset:320
	s_waitcnt lgkmcnt(2)
	v_mfma_f32_32x32x16_bf16 v[66:81], v[214:217], v[114:117], v[66:81]
	ds_read_b128 v[214:217], v205 offset:352
	s_waitcnt lgkmcnt(2)
	v_mfma_f32_32x32x16_bf16 v[66:81], v[218:221], v[118:121], v[66:81]
	s_waitcnt lgkmcnt(1)
	v_mfma_f32_32x32x16_bf16 v[66:81], v[210:213], v[122:125], v[66:81]
	s_waitcnt lgkmcnt(0)
	v_mfma_f32_32x32x16_bf16 v[66:81], v[214:217], v[126:129], v[66:81]
	v_cmp_gt_i32_e32 vcc, s4, v186
	v_subrev_u32_e32 v205, s91, v203
	s_brev_b32 s4, -4
	v_cmp_lt_i32_e64 s[4:5], s4, v205
	s_or_b64 s[4:5], vcc, s[4:5]
	s_and_saveexec_b64 s[58:59], s[4:5]
	s_cbranch_execz .LBB0_769
	v_or_b32_e32 v205, s91, v197
	v_sub_u32_e32 v207, v158, v205
	v_cmp_le_i32_e32 vcc, v205, v158
	v_cmp_gt_i32_e64 s[4:5], 2.0, v207
	s_and_b64 vcc, vcc, s[4:5]
	v_sub_u32_e32 v207, v205, v158
	s_brev_b32 s4, -3
	v_cndmask_b32_e32 v66, v184, v66, vcc
	v_cmp_lt_i32_e32 vcc, v205, v158
	v_cmp_lt_i32_e64 s[4:5], s4, v207
	s_and_b64 vcc, vcc, s[4:5]
	v_or_b32_e32 v207, 2, v205
	v_cndmask_b32_e32 v67, v184, v67, vcc
	v_cmp_ge_i32_e32 vcc, v158, v207
	v_sub_u32_e32 v207, v158, v207
	v_cmp_gt_i32_e64 s[4:5], 2.0, v207
	s_and_b64 vcc, vcc, s[4:5]
	v_or_b32_e32 v207, 3, v205
	v_cndmask_b32_e32 v68, v184, v68, vcc
	v_cmp_ge_i32_e32 vcc, v158, v207
	v_sub_u32_e32 v207, v158, v207
	v_cmp_gt_i32_e64 s[4:5], 2.0, v207
	s_and_b64 vcc, vcc, s[4:5]
	v_or_b32_e32 v207, 8, v205
	v_cndmask_b32_e32 v69, v184, v69, vcc
	v_cmp_ge_i32_e32 vcc, v158, v207
	v_sub_u32_e32 v207, v158, v207
	v_cmp_gt_i32_e64 s[4:5], 2.0, v207
	s_and_b64 vcc, vcc, s[4:5]
	v_or_b32_e32 v207, 9, v205
	v_cndmask_b32_e32 v70, v184, v70, vcc
	v_cmp_ge_i32_e32 vcc, v158, v207
	v_sub_u32_e32 v207, v158, v207
	v_cmp_gt_i32_e64 s[4:5], 2.0, v207
	s_and_b64 vcc, vcc, s[4:5]
	v_or_b32_e32 v207, 10, v205
	v_cndmask_b32_e32 v71, v184, v71, vcc
	v_cmp_ge_i32_e32 vcc, v158, v207
	v_sub_u32_e32 v207, v158, v207
	v_cmp_gt_i32_e64 s[4:5], 2.0, v207
	s_and_b64 vcc, vcc, s[4:5]
	v_or_b32_e32 v207, 11, v205
	v_cndmask_b32_e32 v72, v184, v72, vcc
	v_cmp_ge_i32_e32 vcc, v158, v207
	v_sub_u32_e32 v207, v158, v207
	v_cmp_gt_i32_e64 s[4:5], 2.0, v207
	s_and_b64 vcc, vcc, s[4:5]
	v_or_b32_e32 v207, 16, v205
	v_cndmask_b32_e32 v73, v184, v73, vcc
	v_cmp_ge_i32_e32 vcc, v158, v207
	v_sub_u32_e32 v207, v158, v207
	v_cmp_gt_i32_e64 s[4:5], 2.0, v207
	s_and_b64 vcc, vcc, s[4:5]
	v_or_b32_e32 v207, 17, v205
	v_cndmask_b32_e32 v74, v184, v74, vcc
	v_cmp_ge_i32_e32 vcc, v158, v207
	v_sub_u32_e32 v207, v158, v207
	v_cmp_gt_i32_e64 s[4:5], 2.0, v207
	s_and_b64 vcc, vcc, s[4:5]
	v_or_b32_e32 v207, 18, v205
	v_cndmask_b32_e32 v75, v184, v75, vcc
	v_cmp_ge_i32_e32 vcc, v158, v207
	v_sub_u32_e32 v207, v158, v207
	v_cmp_gt_i32_e64 s[4:5], 2.0, v207
	s_and_b64 vcc, vcc, s[4:5]
	v_or_b32_e32 v207, 19, v205
	v_cndmask_b32_e32 v76, v184, v76, vcc
	v_cmp_ge_i32_e32 vcc, v158, v207
	v_sub_u32_e32 v207, v158, v207
	v_cmp_gt_i32_e64 s[4:5], 2.0, v207
	s_and_b64 vcc, vcc, s[4:5]
	v_or_b32_e32 v207, 24, v205
	v_cndmask_b32_e32 v77, v184, v77, vcc
	v_cmp_ge_i32_e32 vcc, v158, v207
	v_sub_u32_e32 v207, v158, v207
	v_cmp_gt_i32_e64 s[4:5], 2.0, v207
	s_and_b64 vcc, vcc, s[4:5]
	v_or_b32_e32 v207, 25, v205
	v_cndmask_b32_e32 v78, v184, v78, vcc
	v_cmp_ge_i32_e32 vcc, v158, v207
	v_sub_u32_e32 v207, v158, v207
	v_cmp_gt_i32_e64 s[4:5], 2.0, v207
	s_and_b64 vcc, vcc, s[4:5]
	v_or_b32_e32 v207, 26, v205
	v_cndmask_b32_e32 v79, v184, v79, vcc
	v_cmp_ge_i32_e32 vcc, v158, v207
	v_sub_u32_e32 v207, v158, v207
	v_cmp_gt_i32_e64 s[4:5], 2.0, v207
	s_and_b64 vcc, vcc, s[4:5]
	v_or_b32_e32 v205, 27, v205
	v_cndmask_b32_e32 v80, v184, v80, vcc
	v_cmp_ge_i32_e32 vcc, v158, v205
	v_sub_u32_e32 v205, v158, v205
	v_cmp_gt_i32_e64 s[4:5], 2.0, v205
	s_and_b64 vcc, vcc, s[4:5]
	v_cndmask_b32_e32 v81, v184, v81, vcc
	s_branch .LBB0_769
.Lmla_fast:
	s_mul_i32 s5, s90, 0x3200
	v_add_u32_e32 v205, s5, v204
	v_add3_u32 v247, v209, v0, v200
	ds_read_b128 v[226:229], v205
	ds_read_b128 v[230:233], v205 offset:32
	ds_read_b128 v[234:237], v205 offset:64
	ds_read_b128 v[238:241], v205 offset:96
	s_lshl_b32 s4, s90, 6
	s_add_i32 s4, s89, s4
	s_add_i32 s4, s4, 0xc800
	v_mov_b32_e32 v209, s4
	s_cmp_lg_u32 s20, 0
	s_cbranch_scc1 .Lmla_negm_ok
	v_sub_f32_e32 v210, 0, v206
	v_sub_f32_e32 v211, 0, v206
	v_sub_f32_e32 v212, 0, v206
	v_sub_f32_e32 v213, 0, v206
	v_sub_f32_e32 v214, 0, v206
	v_sub_f32_e32 v215, 0, v206
	v_sub_f32_e32 v216, 0, v206
	v_sub_f32_e32 v217, 0, v206
	v_sub_f32_e32 v218, 0, v206
	v_sub_f32_e32 v219, 0, v206
	v_sub_f32_e32 v220, 0, v206
	v_sub_f32_e32 v221, 0, v206
	v_sub_f32_e32 v222, 0, v206
	v_sub_f32_e32 v223, 0, v206
	v_sub_f32_e32 v224, 0, v206
	v_sub_f32_e32 v225, 0, v206
	s_mov_b32 s20, 1
	s_nop 1
.Lmla_negm_ok:
	s_waitcnt lgkmcnt(3)
	v_mfma_f32_32x32x16_bf16 v[66:81], v[226:229], v[82:85], v[210:225]
	ds_read_b128 v[242:245], v205 offset:128
	s_waitcnt lgkmcnt(3)
	v_mfma_f32_32x32x16_bf16 v[66:81], v[230:233], v[86:89], v[66:81]
	ds_read_b128 v[226:229], v205 offset:160
	s_waitcnt lgkmcnt(3)
	v_mfma_f32_32x32x16_bf16 v[66:81], v[234:237], v[90:93], v[66:81]
	ds_read_b128 v[230:233], v205 offset:192
	s_waitcnt lgkmcnt(3)
	v_mfma_f32_32x32x16_bf16 v[66:81], v[238:241], v[94:97], v[66:81]
	ds_read_b128 v[234:237], v205 offset:224
	s_waitcnt lgkmcnt(3)
	v_mfma_f32_32x32x16_bf16 v[66:81], v[242:245], v[98:101], v[66:81]
	ds_read_b128 v[238:241], v205 offset:256
	s_waitcnt lgkmcnt(3)
	v_mfma_f32_32x32x16_bf16 v[66:81], v[226:229], v[102:105], v[66:81]
	ds_read_b128 v[242:245], v205 offset:288
	s_waitcnt lgkmcnt(3)
	v_mfma_f32_32x32x16_bf16 v[66:81], v[230:233], v[106:109], v[66:81]
	ds_read_b128 v[226:229], v205 offset:320
	s_waitcnt lgkmcnt(3)
	v_mfma_f32_32x32x16_bf16 v[66:81], v[234:237], v[110:113], v[66:81]
	ds_read_b128 v[230:233], v205 offset:352
	s_waitcnt lgkmcnt(3)
	v_mfma_f32_32x32x16_bf16 v[66:81], v[238:241], v[114:117], v[66:81]
	ds_read_b128 v[234:237], v247
	s_waitcnt lgkmcnt(3)
	v_mfma_f32_32x32x16_bf16 v[66:81], v[242:245], v[118:121], v[66:81]
	ds_read_b128 v[238:241], v247 offset:4608
	s_waitcnt lgkmcnt(3)
	v_mfma_f32_32x32x16_bf16 v[66:81], v[226:229], v[122:125], v[66:81]
	ds_read_b128 v[242:245], v247 offset:9216
	s_waitcnt lgkmcnt(3)
	v_mfma_f32_32x32x16_bf16 v[66:81], v[230:233], v[126:129], v[66:81]
	ds_read_b128 v[226:229], v247 offset:13824
	s_waitcnt lgkmcnt(3)
	v_mfma_f32_32x32x16_bf16 v[50:65], v[234:237], v[154:157], v[50:65]
	ds_read_b128 v[230:233], v247 offset:32
	s_waitcnt lgkmcnt(3)
	v_mfma_f32_32x32x16_bf16 v[34:49], v[238:241], v[154:157], v[34:49]
	ds_read_b128 v[234:237], v247 offset:4640
	s_waitcnt lgkmcnt(3)
	v_mfma_f32_32x32x16_bf16 v[18:33], v[242:245], v[154:157], v[18:33]
	ds_read_b128 v[238:241], v247 offset:9248
	s_waitcnt lgkmcnt(3)
	v_mfma_f32_32x32x16_bf16 v[2:17], v[226:229], v[154:157], v[2:17]
	ds_read_b128 v[242:245], v247 offset:13856
	s_waitcnt lgkmcnt(3)
	v_mfma_f32_32x32x16_bf16 v[50:65], v[230:233], v[150:153], v[50:65]
	s_waitcnt lgkmcnt(2)
	v_mfma_f32_32x32x16_bf16 v[34:49], v[234:237], v[150:153], v[34:49]
	s_waitcnt lgkmcnt(1)
	v_mfma_f32_32x32x16_bf16 v[18:33], v[238:241], v[150:153], v[18:33]
	s_waitcnt lgkmcnt(0)
	v_mfma_f32_32x32x16_bf16 v[2:17], v[242:245], v[150:153], v[2:17]
	v_max3_f32 v207, v66, v67, v68
	v_max3_f32 v208, v74, v75, v76
	v_max3_f32 v207, v207, v69, v70
	v_max3_f32 v208, v208, v77, v78
	v_max3_f32 v207, v207, v71, v72
	v_max3_f32 v208, v208, v79, v80
	v_max3_f32 v207, v207, v73, v81
	v_max_f32_e32 v207, v207, v208
	v_cmp_lt_f32_e32 vcc, 0x41000000, v207
	s_cbranch_vccnz .Lmla_grow
.Lmla_exp:
	v_exp_f32_e32 v66, v66
	v_exp_f32_e32 v67, v67
	v_exp_f32_e32 v68, v68
	v_add_f32_e32 v248, v67, v66
	v_exp_f32_e32 v69, v69
	v_add_f32_e32 v248, v68, v248
	v_exp_f32_e32 v70, v70
	v_add_f32_e32 v248, v69, v248
	v_exp_f32_e32 v71, v71
	v_add_f32_e32 v248, v70, v248
	v_exp_f32_e32 v72, v72
	v_add_f32_e32 v248, v71, v248
	v_exp_f32_e32 v73, v73
	v_add_f32_e32 v248, v72, v248
	v_exp_f32_e32 v74, v74
	v_add_f32_e32 v248, v73, v248
	v_exp_f32_e32 v75, v75
	v_add_f32_e32 v248, v74, v248
	v_exp_f32_e32 v76, v76
	v_add_f32_e32 v248, v75, v248
	v_exp_f32_e32 v77, v77
	v_add_f32_e32 v248, v76, v248
	v_exp_f32_e32 v78, v78
	v_add_f32_e32 v248, v77, v248
	v_exp_f32_e32 v79, v79
	v_add_f32_e32 v248, v78, v248
	v_exp_f32_e32 v80, v80
	v_add_f32_e32 v248, v79, v248
	v_exp_f32_e32 v81, v81
	v_add_f32_e32 v248, v80, v248
	s_nop 0
	v_add_f32_e32 v248, v81, v248
	v_cvt_pk_bf16_f32 v154, v66, v67
	v_cvt_pk_bf16_f32 v155, v68, v69
	v_cvt_pk_bf16_f32 v156, v70, v71
	v_cvt_pk_bf16_f32 v157, v72, v73
	v_cvt_pk_bf16_f32 v150, v74, v75
	v_cvt_pk_bf16_f32 v151, v76, v77
	v_cvt_pk_bf16_f32 v152, v78, v79
	v_cvt_pk_bf16_f32 v153, v80, v81
	v_add_f32_e32 v199, v199, v248
	s_branch .Lmla_tail
.Lmla_grow:
	v_mov_b32_e32 v208, v207
	s_nop 1
	v_permlane32_swap_b32_e32 v207, v208
	v_max_f32_e32 v207, v207, v208
	v_max_f32_e32 v207, 0, v207
	v_sub_f32_e32 v250, 0, v207
	v_add_f32_e32 v206, v206, v207
	v_exp_f32_e32 v250, v250
	v_sub_f32_e32 v66, v66, v207
	v_sub_f32_e32 v67, v67, v207
	v_sub_f32_e32 v68, v68, v207
	v_sub_f32_e32 v69, v69, v207
	v_sub_f32_e32 v70, v70, v207
	v_sub_f32_e32 v71, v71, v207
	v_sub_f32_e32 v72, v72, v207
	v_sub_f32_e32 v73, v73, v207
	v_sub_f32_e32 v74, v74, v207
	v_sub_f32_e32 v75, v75, v207
	v_sub_f32_e32 v76, v76, v207
	v_sub_f32_e32 v77, v77, v207
	v_sub_f32_e32 v78, v78, v207
	v_sub_f32_e32 v79, v79, v207
	v_sub_f32_e32 v80, v80, v207
	v_sub_f32_e32 v81, v81, v207
	v_sub_f32_e32 v210, 0, v206
	v_sub_f32_e32 v211, 0, v206
	v_sub_f32_e32 v212, 0, v206
	v_sub_f32_e32 v213, 0, v206
	v_sub_f32_e32 v214, 0, v206
	v_sub_f32_e32 v215, 0, v206
	v_sub_f32_e32 v216, 0, v206
	v_sub_f32_e32 v217, 0, v206
	v_sub_f32_e32 v218, 0, v206
	v_sub_f32_e32 v219, 0, v206
	v_sub_f32_e32 v220, 0, v206
	v_sub_f32_e32 v221, 0, v206
	v_sub_f32_e32 v222, 0, v206
	v_sub_f32_e32 v223, 0, v206
	v_sub_f32_e32 v224, 0, v206
	v_sub_f32_e32 v225, 0, v206
	v_mul_f32_e32 v199, v199, v250
	v_pk_mul_f32 v[64:65], v[64:65], v[250:251] op_sel_hi:[1,0]
	v_pk_mul_f32 v[62:63], v[62:63], v[250:251] op_sel_hi:[1,0]
	v_pk_mul_f32 v[60:61], v[60:61], v[250:251] op_sel_hi:[1,0]
	v_pk_mul_f32 v[58:59], v[58:59], v[250:251] op_sel_hi:[1,0]
	v_pk_mul_f32 v[56:57], v[56:57], v[250:251] op_sel_hi:[1,0]
	v_pk_mul_f32 v[54:55], v[54:55], v[250:251] op_sel_hi:[1,0]
	v_pk_mul_f32 v[52:53], v[52:53], v[250:251] op_sel_hi:[1,0]
	v_pk_mul_f32 v[50:51], v[50:51], v[250:251] op_sel_hi:[1,0]
	v_pk_mul_f32 v[48:49], v[48:49], v[250:251] op_sel_hi:[1,0]
	v_pk_mul_f32 v[46:47], v[46:47], v[250:251] op_sel_hi:[1,0]
	v_pk_mul_f32 v[44:45], v[44:45], v[250:251] op_sel_hi:[1,0]
	v_pk_mul_f32 v[42:43], v[42:43], v[250:251] op_sel_hi:[1,0]
	v_pk_mul_f32 v[40:41], v[40:41], v[250:251] op_sel_hi:[1,0]
	v_pk_mul_f32 v[38:39], v[38:39], v[250:251] op_sel_hi:[1,0]
	v_pk_mul_f32 v[36:37], v[36:37], v[250:251] op_sel_hi:[1,0]
	v_pk_mul_f32 v[34:35], v[34:35], v[250:251] op_sel_hi:[1,0]
	v_pk_mul_f32 v[32:33], v[32:33], v[250:251] op_sel_hi:[1,0]
	v_pk_mul_f32 v[30:31], v[30:31], v[250:251] op_sel_hi:[1,0]
	v_pk_mul_f32 v[28:29], v[28:29], v[250:251] op_sel_hi:[1,0]
	v_pk_mul_f32 v[26:27], v[26:27], v[250:251] op_sel_hi:[1,0]
	v_pk_mul_f32 v[24:25], v[24:25], v[250:251] op_sel_hi:[1,0]
	v_pk_mul_f32 v[22:23], v[22:23], v[250:251] op_sel_hi:[1,0]
	v_pk_mul_f32 v[20:21], v[20:21], v[250:251] op_sel_hi:[1,0]
	v_pk_mul_f32 v[18:19], v[18:19], v[250:251] op_sel_hi:[1,0]
	v_pk_mul_f32 v[16:17], v[16:17], v[250:251] op_sel_hi:[1,0]
	v_pk_mul_f32 v[14:15], v[14:15], v[250:251] op_sel_hi:[1,0]
	v_pk_mul_f32 v[12:13], v[12:13], v[250:251] op_sel_hi:[1,0]
	v_pk_mul_f32 v[10:11], v[10:11], v[250:251] op_sel_hi:[1,0]
	v_pk_mul_f32 v[8:9], v[8:9], v[250:251] op_sel_hi:[1,0]
	v_pk_mul_f32 v[6:7], v[6:7], v[250:251] op_sel_hi:[1,0]
	v_pk_mul_f32 v[4:5], v[4:5], v[250:251] op_sel_hi:[1,0]
	v_pk_mul_f32 v[2:3], v[2:3], v[250:251] op_sel_hi:[1,0]
	s_branch .Lmla_exp

	.amdhsa_kernel _Z14fwd_megakernel6Params
		.amdhsa_group_segment_fixed_size 1024
		.amdhsa_private_segment_fixed_size 0
		.amdhsa_kernarg_size 456
		.amdhsa_user_sgpr_count 2
		.amdhsa_user_sgpr_dispatch_ptr 0
		.amdhsa_user_sgpr_queue_ptr 0
		.amdhsa_user_sgpr_kernarg_segment_ptr 1
		.amdhsa_user_sgpr_dispatch_id 0
		.amdhsa_user_sgpr_kernarg_preload_length 0
		.amdhsa_user_sgpr_kernarg_preload_offset 0
		.amdhsa_user_sgpr_private_segment_size 0
		.amdhsa_uses_dynamic_stack 0
		.amdhsa_enable_private_segment 0
		.amdhsa_system_sgpr_workgroup_id_x 1
		.amdhsa_system_sgpr_workgroup_id_y 0
		.amdhsa_system_sgpr_workgroup_id_z 0
		.amdhsa_system_sgpr_workgroup_info 0
		.amdhsa_system_vgpr_workitem_id 2
		.amdhsa_next_free_vgpr 256
		.amdhsa_next_free_sgpr 102
		.amdhsa_accum_offset 256
		.amdhsa_reserve_vcc 1
		.amdhsa_float_round_mode_32 0
		.amdhsa_float_round_mode_16_64 0
		.amdhsa_float_denorm_mode_32 3
		.amdhsa_float_denorm_mode_16_64 3
		.amdhsa_dx10_clamp 1
		.amdhsa_ieee_mode 1
		.amdhsa_fp16_overflow 0
		.amdhsa_tg_split 0
		.amdhsa_exception_fp_ieee_invalid_op 0
		.amdhsa_exception_fp_denorm_src 0
		.amdhsa_exception_fp_ieee_div_zero 0
		.amdhsa_exception_fp_ieee_overflow 0
		.amdhsa_exception_fp_ieee_underflow 0
		.amdhsa_exception_fp_ieee_inexact 0
		.amdhsa_exception_int_div_zero 0
	.end_amdhsa_kernel

amdhsa.kernels:
  - .agpr_count:     0
    .args:
      - .offset:         0
        .size:           200
        .value_kind:     by_value
      - .offset:         200
        .size:           4
        .value_kind:     hidden_block_count_x
      - .offset:         204
        .size:           4
        .value_kind:     hidden_block_count_y
      - .offset:         208
        .size:           4
        .value_kind:     hidden_block_count_z
      - .offset:         212
        .size:           2
        .value_kind:     hidden_group_size_x
      - .offset:         214
        .size:           2
        .value_kind:     hidden_group_size_y
      - .offset:         216
        .size:           2
        .value_kind:     hidden_group_size_z
      - .offset:         218
        .size:           2
        .value_kind:     hidden_remainder_x
      - .offset:         220
        .size:           2
        .value_kind:     hidden_remainder_y
      - .offset:         222
        .size:           2
        .value_kind:     hidden_remainder_z
      - .offset:         240
        .size:           8
        .value_kind:     hidden_global_offset_x
      - .offset:         248
        .size:           8
        .value_kind:     hidden_global_offset_y
      - .offset:         256
        .size:           8
        .value_kind:     hidden_global_offset_z
      - .offset:         264
        .size:           2
        .value_kind:     hidden_grid_dims
      - .offset:         288
        .size:           8
        .value_kind:     hidden_multigrid_sync_arg
      - .offset:         320
        .size:           4
        .value_kind:     hidden_dynamic_lds_size
    .group_segment_fixed_size: 1024
    .kernarg_segment_align: 8
    .kernarg_segment_size: 456
    .language:       OpenCL C
    .language_version:
      - 2
      - 0
    .max_flat_workgroup_size: 512
    .name:           _Z14fwd_megakernel6Params
    .private_segment_fixed_size: 0
    .sgpr_count:     108
    .sgpr_spill_count: 60
    .symbol:         _Z14fwd_megakernel6Params.kd
    .uniform_work_group_size: 1
    .uses_dynamic_stack: false
    .vgpr_count:     256
    .vgpr_spill_count: 0
    .wavefront_size: 64
